# main GEMM k-loop restructured to 4 phases per k-step (32 MFMAs per barrier pair, all fragment reads of a phase issued together)
# speedup vs baseline: 1.0217x; 1.0172x over previous
.LBB0_372:
	s_add_u32 s8, s6, 0xfff80080
	s_addc_u32 s9, s7, -1
	s_add_i32 s21, 0, 0x10000
	v_add_u32_e32 v143, s21, v167
	ds_read_b128 v[148:151], v143
	ds_read_b128 v[152:155], v143 offset:1024
	ds_read_b128 v[156:159], v143 offset:2048
	ds_read_b128 v[160:163], v143 offset:3072
	s_cmp_eq_u32 s20, 28
	s_cselect_b32 s11, s17, s9
	s_cselect_b32 s10, s16, s8
	s_cselect_b32 s9, s19, s15
	s_cselect_b32 s8, s18, s13
	s_add_i32 s24, 0, 0x14000
	v_add_u32_e32 v143, s24, v167
	ds_read_b128 v[208:211], v143
	ds_read_b128 v[212:215], v143 offset:1024
	ds_read_b128 v[216:219], v143 offset:2048
	ds_read_b128 v[220:223], v143 offset:3072
	v_lshl_add_u64 v[164:165], s[6:7], 0, v[138:139]
	s_add_i32 m0, s40, 0xc000
	ds_read_b128 v[172:175], v171
	ds_read_b128 v[180:183], v171 offset:1024
	ds_read_b128 v[184:187], v171 offset:2048
	ds_read_b128 v[188:191], v171 offset:3072
	ds_read_b128 v[192:195], v171 offset:4096
	ds_read_b128 v[196:199], v171 offset:5120
	ds_read_b128 v[200:203], v171 offset:6144
	ds_read_b128 v[204:207], v171 offset:7168
	global_load_lds_dwordx4 v[164:165], off
	v_lshl_add_u64 v[164:165], s[6:7], 0, v[140:141]
	s_add_i32 m0, s40, 0xe000
	s_nop 0
	global_load_lds_dwordx4 v[164:165], off
	s_waitcnt lgkmcnt(0)
	s_barrier
	s_setprio 1
	v_mfma_f32_16x16x32_bf16 v[126:129], v[148:151], v[172:175], v[126:129]
	v_mfma_f32_16x16x32_bf16 v[122:125], v[156:159], v[172:175], v[122:125]
	v_mfma_f32_16x16x32_bf16 v[110:113], v[148:151], v[184:187], v[110:113]
	v_mfma_f32_16x16x32_bf16 v[106:109], v[156:159], v[184:187], v[106:109]
	v_mfma_f32_16x16x32_bf16 v[94:97], v[148:151], v[192:195], v[94:97]
	v_mfma_f32_16x16x32_bf16 v[90:93], v[156:159], v[192:195], v[90:93]
	v_mfma_f32_16x16x32_bf16 v[78:81], v[148:151], v[200:203], v[78:81]
	v_mfma_f32_16x16x32_bf16 v[74:77], v[156:159], v[200:203], v[74:77]
	v_mfma_f32_16x16x32_bf16 v[126:129], v[152:155], v[180:183], v[126:129]
	v_mfma_f32_16x16x32_bf16 v[122:125], v[160:163], v[180:183], v[122:125]
	v_mfma_f32_16x16x32_bf16 v[110:113], v[152:155], v[188:191], v[110:113]
	v_mfma_f32_16x16x32_bf16 v[106:109], v[160:163], v[188:191], v[106:109]
	v_mfma_f32_16x16x32_bf16 v[94:97], v[152:155], v[196:199], v[94:97]
	v_mfma_f32_16x16x32_bf16 v[90:93], v[160:163], v[196:199], v[90:93]
	v_mfma_f32_16x16x32_bf16 v[78:81], v[152:155], v[204:207], v[78:81]
	v_mfma_f32_16x16x32_bf16 v[74:77], v[160:163], v[204:207], v[74:77]
	v_mfma_f32_16x16x32_bf16 v[118:121], v[208:211], v[172:175], v[118:121]
	v_mfma_f32_16x16x32_bf16 v[114:117], v[216:219], v[172:175], v[114:117]
	v_mfma_f32_16x16x32_bf16 v[102:105], v[208:211], v[184:187], v[102:105]
	v_mfma_f32_16x16x32_bf16 v[98:101], v[216:219], v[184:187], v[98:101]
	v_mfma_f32_16x16x32_bf16 v[86:89], v[208:211], v[192:195], v[86:89]
	v_mfma_f32_16x16x32_bf16 v[82:85], v[216:219], v[192:195], v[82:85]
	v_mfma_f32_16x16x32_bf16 v[70:73], v[208:211], v[200:203], v[70:73]
	v_mfma_f32_16x16x32_bf16 v[66:69], v[216:219], v[200:203], v[66:69]
	v_mfma_f32_16x16x32_bf16 v[118:121], v[212:215], v[180:183], v[118:121]
	v_mfma_f32_16x16x32_bf16 v[114:117], v[220:223], v[180:183], v[114:117]
	v_mfma_f32_16x16x32_bf16 v[102:105], v[212:215], v[188:191], v[102:105]
	v_mfma_f32_16x16x32_bf16 v[98:101], v[220:223], v[188:191], v[98:101]
	v_mfma_f32_16x16x32_bf16 v[86:89], v[212:215], v[196:199], v[86:89]
	v_mfma_f32_16x16x32_bf16 v[82:85], v[220:223], v[196:199], v[82:85]
	v_mfma_f32_16x16x32_bf16 v[70:73], v[212:215], v[204:207], v[70:73]
	v_mfma_f32_16x16x32_bf16 v[66:69], v[220:223], v[204:207], v[66:69]
	s_setprio 0
	s_mov_b32 m0, s40
	v_lshl_add_u64 v[224:225], s[10:11], 0, v[136:137]
	s_barrier
	ds_read_b128 v[172:175], v171 offset:16384
	ds_read_b128 v[180:183], v171 offset:17408
	ds_read_b128 v[184:187], v171 offset:18432
	ds_read_b128 v[188:191], v171 offset:19456
	ds_read_b128 v[192:195], v171 offset:20480
	ds_read_b128 v[196:199], v171 offset:21504
	ds_read_b128 v[200:203], v171 offset:22528
	ds_read_b128 v[204:207], v171 offset:23552
	s_add_i32 s21, s21, s39
	v_lshl_add_u64 v[164:165], s[8:9], 0, v[134:135]
	s_mov_b32 m0, s21
	s_nop 0
	global_load_lds_dwordx4 v[164:165], off
	v_lshl_add_u64 v[176:177], s[8:9], 0, v[130:131]
	s_add_i32 m0, s21, 0x2000
	s_nop 0
	global_load_lds_dwordx4 v[176:177], off
	s_mov_b32 m0, s40
	s_nop 0
	global_load_lds_dwordx4 v[224:225], off
	v_lshl_add_u64 v[236:237], s[10:11], 0, v[132:133]
	s_mov_b32 m0, s41
	s_nop 0
	global_load_lds_dwordx4 v[236:237], off
	s_add_u32 s22, s8, 0x80000
	s_addc_u32 s23, s9, 0
	s_add_i32 s21, s24, s39
	s_mov_b32 m0, s21
	s_nop 0
	global_load_lds_dwordx4 v134, s[22:23]
	s_add_i32 m0, s21, 0x2000
	s_nop 0
	global_load_lds_dwordx4 v130, s[22:23]
	s_waitcnt vmcnt(6)
	s_waitcnt lgkmcnt(0)
	s_barrier
	s_setprio 1
	v_mfma_f32_16x16x32_bf16 v[62:65], v[148:151], v[172:175], v[62:65]
	v_mfma_f32_16x16x32_bf16 v[58:61], v[156:159], v[172:175], v[58:61]
	v_mfma_f32_16x16x32_bf16 v[46:49], v[148:151], v[184:187], v[46:49]
	v_mfma_f32_16x16x32_bf16 v[42:45], v[156:159], v[184:187], v[42:45]
	v_mfma_f32_16x16x32_bf16 v[28:31], v[148:151], v[192:195], v[28:31]
	v_mfma_f32_16x16x32_bf16 v[24:27], v[156:159], v[192:195], v[24:27]
	v_mfma_f32_16x16x32_bf16 v[12:15], v[148:151], v[200:203], v[12:15]
	v_mfma_f32_16x16x32_bf16 v[8:11], v[156:159], v[200:203], v[8:11]
	v_mfma_f32_16x16x32_bf16 v[62:65], v[152:155], v[180:183], v[62:65]
	v_mfma_f32_16x16x32_bf16 v[58:61], v[160:163], v[180:183], v[58:61]
	v_mfma_f32_16x16x32_bf16 v[46:49], v[152:155], v[188:191], v[46:49]
	v_mfma_f32_16x16x32_bf16 v[42:45], v[160:163], v[188:191], v[42:45]
	v_mfma_f32_16x16x32_bf16 v[28:31], v[152:155], v[196:199], v[28:31]
	v_mfma_f32_16x16x32_bf16 v[24:27], v[160:163], v[196:199], v[24:27]
	v_mfma_f32_16x16x32_bf16 v[12:15], v[152:155], v[204:207], v[12:15]
	v_mfma_f32_16x16x32_bf16 v[8:11], v[160:163], v[204:207], v[8:11]
	v_mfma_f32_16x16x32_bf16 v[54:57], v[208:211], v[172:175], v[54:57]
	v_mfma_f32_16x16x32_bf16 v[50:53], v[216:219], v[172:175], v[50:53]
	v_mfma_f32_16x16x32_bf16 v[38:41], v[208:211], v[184:187], v[38:41]
	v_mfma_f32_16x16x32_bf16 v[34:37], v[216:219], v[184:187], v[34:37]
	v_mfma_f32_16x16x32_bf16 v[20:23], v[208:211], v[192:195], v[20:23]
	v_mfma_f32_16x16x32_bf16 v[16:19], v[216:219], v[192:195], v[16:19]
	v_mfma_f32_16x16x32_bf16 v[4:7], v[208:211], v[200:203], v[4:7]
	v_mfma_f32_16x16x32_bf16 v[0:3], v[216:219], v[200:203], v[0:3]
	v_mfma_f32_16x16x32_bf16 v[54:57], v[212:215], v[180:183], v[54:57]
	v_mfma_f32_16x16x32_bf16 v[50:53], v[220:223], v[180:183], v[50:53]
	v_mfma_f32_16x16x32_bf16 v[38:41], v[212:215], v[188:191], v[38:41]
	v_mfma_f32_16x16x32_bf16 v[34:37], v[220:223], v[188:191], v[34:37]
	v_mfma_f32_16x16x32_bf16 v[20:23], v[212:215], v[196:199], v[20:23]
	v_mfma_f32_16x16x32_bf16 v[16:19], v[220:223], v[196:199], v[16:19]
	v_mfma_f32_16x16x32_bf16 v[4:7], v[212:215], v[204:207], v[4:7]
	v_mfma_f32_16x16x32_bf16 v[0:3], v[220:223], v[204:207], v[0:3]
	s_setprio 0
	s_add_i32 s21, 0, 0x18000
	v_add_u32_e32 v143, s21, v167
	s_barrier
	ds_read_b128 v[148:151], v143
	ds_read_b128 v[152:155], v143 offset:1024
	ds_read_b128 v[156:159], v143 offset:2048
	ds_read_b128 v[160:163], v143 offset:3072
	s_add_u32 s10, s10, 0x80000
	s_addc_u32 s11, s11, 0
	s_add_i32 s22, 0, 0x1c000
	v_add_u32_e32 v143, s22, v167
	ds_read_b128 v[208:211], v143
	ds_read_b128 v[212:215], v143 offset:1024
	ds_read_b128 v[216:219], v143 offset:2048
	ds_read_b128 v[220:223], v143 offset:3072
	s_mov_b32 m0, s42
	s_nop 0
	global_load_lds_dwordx4 v136, s[10:11]
	ds_read_b128 v[172:175], v171 offset:32768
	ds_read_b128 v[180:183], v171 offset:33792
	ds_read_b128 v[184:187], v171 offset:34816
	ds_read_b128 v[188:191], v171 offset:35840
	ds_read_b128 v[192:195], v171 offset:36864
	ds_read_b128 v[196:199], v171 offset:37888
	ds_read_b128 v[200:203], v171 offset:38912
	ds_read_b128 v[204:207], v171 offset:39936
	s_mov_b32 m0, s43
	s_nop 0
	global_load_lds_dwordx4 v132, s[10:11]
	s_waitcnt lgkmcnt(0)
	s_barrier
	s_setprio 1
	v_mfma_f32_16x16x32_bf16 v[126:129], v[148:151], v[172:175], v[126:129]
	v_mfma_f32_16x16x32_bf16 v[122:125], v[156:159], v[172:175], v[122:125]
	v_mfma_f32_16x16x32_bf16 v[110:113], v[148:151], v[184:187], v[110:113]
	v_mfma_f32_16x16x32_bf16 v[106:109], v[156:159], v[184:187], v[106:109]
	v_mfma_f32_16x16x32_bf16 v[94:97], v[148:151], v[192:195], v[94:97]
	v_mfma_f32_16x16x32_bf16 v[90:93], v[156:159], v[192:195], v[90:93]
	v_mfma_f32_16x16x32_bf16 v[78:81], v[148:151], v[200:203], v[78:81]
	v_mfma_f32_16x16x32_bf16 v[74:77], v[156:159], v[200:203], v[74:77]
	v_mfma_f32_16x16x32_bf16 v[126:129], v[152:155], v[180:183], v[126:129]
	v_mfma_f32_16x16x32_bf16 v[122:125], v[160:163], v[180:183], v[122:125]
	v_mfma_f32_16x16x32_bf16 v[110:113], v[152:155], v[188:191], v[110:113]
	v_mfma_f32_16x16x32_bf16 v[106:109], v[160:163], v[188:191], v[106:109]
	v_mfma_f32_16x16x32_bf16 v[94:97], v[152:155], v[196:199], v[94:97]
	v_mfma_f32_16x16x32_bf16 v[90:93], v[160:163], v[196:199], v[90:93]
	v_mfma_f32_16x16x32_bf16 v[78:81], v[152:155], v[204:207], v[78:81]
	v_mfma_f32_16x16x32_bf16 v[74:77], v[160:163], v[204:207], v[74:77]
	v_mfma_f32_16x16x32_bf16 v[118:121], v[208:211], v[172:175], v[118:121]
	v_mfma_f32_16x16x32_bf16 v[114:117], v[216:219], v[172:175], v[114:117]
	v_mfma_f32_16x16x32_bf16 v[102:105], v[208:211], v[184:187], v[102:105]
	v_mfma_f32_16x16x32_bf16 v[98:101], v[216:219], v[184:187], v[98:101]
	v_mfma_f32_16x16x32_bf16 v[86:89], v[208:211], v[192:195], v[86:89]
	v_mfma_f32_16x16x32_bf16 v[82:85], v[216:219], v[192:195], v[82:85]
	v_mfma_f32_16x16x32_bf16 v[70:73], v[208:211], v[200:203], v[70:73]
	v_mfma_f32_16x16x32_bf16 v[66:69], v[216:219], v[200:203], v[66:69]
	v_mfma_f32_16x16x32_bf16 v[118:121], v[212:215], v[180:183], v[118:121]
	v_mfma_f32_16x16x32_bf16 v[114:117], v[220:223], v[180:183], v[114:117]
	v_mfma_f32_16x16x32_bf16 v[102:105], v[212:215], v[188:191], v[102:105]
	v_mfma_f32_16x16x32_bf16 v[98:101], v[220:223], v[188:191], v[98:101]
	v_mfma_f32_16x16x32_bf16 v[86:89], v[212:215], v[196:199], v[86:89]
	v_mfma_f32_16x16x32_bf16 v[82:85], v[220:223], v[196:199], v[82:85]
	v_mfma_f32_16x16x32_bf16 v[70:73], v[212:215], v[204:207], v[70:73]
	v_mfma_f32_16x16x32_bf16 v[66:69], v[220:223], v[204:207], v[66:69]
	s_setprio 0
	s_barrier
	ds_read_b128 v[172:175], v171 offset:49152
	ds_read_b128 v[180:183], v171 offset:50176
	ds_read_b128 v[184:187], v171 offset:51200
	ds_read_b128 v[188:191], v171 offset:52224
	ds_read_b128 v[192:195], v171 offset:53248
	ds_read_b128 v[196:199], v171 offset:54272
	ds_read_b128 v[200:203], v171 offset:55296
	ds_read_b128 v[204:207], v171 offset:56320
	s_add_i32 s11, s21, s39
	v_lshl_add_u64 v[164:165], v[164:165], 0, s[88:89]
	s_mov_b32 m0, s11
	s_nop 0
	global_load_lds_dwordx4 v[164:165], off
	v_lshl_add_u64 v[164:165], v[176:177], 0, s[88:89]
	s_add_i32 m0, s11, 0x2000
	s_nop 0
	global_load_lds_dwordx4 v[164:165], off
	s_mov_b32 m0, s46
	v_lshl_add_u64 v[164:165], v[224:225], 0, s[88:89]
	s_nop 0
	global_load_lds_dwordx4 v[164:165], off
	v_lshl_add_u64 v[164:165], v[236:237], 0, s[88:89]
	s_mov_b32 m0, s47
	s_nop 0
	global_load_lds_dwordx4 v[164:165], off
	s_add_u32 s8, s8, 0x80080
	s_addc_u32 s9, s9, 0
	s_add_i32 s10, s39, 0x1c000
	s_mov_b32 m0, s10
	s_nop 0
	global_load_lds_dwordx4 v134, s[8:9]
	s_add_i32 m0, s10, 0x2000
	s_nop 0
	global_load_lds_dwordx4 v130, s[8:9]
	s_waitcnt vmcnt(6)
	s_waitcnt lgkmcnt(0)
	s_barrier
	s_setprio 1
	v_mfma_f32_16x16x32_bf16 v[62:65], v[148:151], v[172:175], v[62:65]
	v_mfma_f32_16x16x32_bf16 v[58:61], v[156:159], v[172:175], v[58:61]
	v_mfma_f32_16x16x32_bf16 v[46:49], v[148:151], v[184:187], v[46:49]
	v_mfma_f32_16x16x32_bf16 v[42:45], v[156:159], v[184:187], v[42:45]
	v_mfma_f32_16x16x32_bf16 v[28:31], v[148:151], v[192:195], v[28:31]
	v_mfma_f32_16x16x32_bf16 v[24:27], v[156:159], v[192:195], v[24:27]
	v_mfma_f32_16x16x32_bf16 v[12:15], v[148:151], v[200:203], v[12:15]
	v_mfma_f32_16x16x32_bf16 v[8:11], v[156:159], v[200:203], v[8:11]
	v_mfma_f32_16x16x32_bf16 v[62:65], v[152:155], v[180:183], v[62:65]
	v_mfma_f32_16x16x32_bf16 v[58:61], v[160:163], v[180:183], v[58:61]
	v_mfma_f32_16x16x32_bf16 v[46:49], v[152:155], v[188:191], v[46:49]
	v_mfma_f32_16x16x32_bf16 v[42:45], v[160:163], v[188:191], v[42:45]
	v_mfma_f32_16x16x32_bf16 v[28:31], v[152:155], v[196:199], v[28:31]
	v_mfma_f32_16x16x32_bf16 v[24:27], v[160:163], v[196:199], v[24:27]
	v_mfma_f32_16x16x32_bf16 v[12:15], v[152:155], v[204:207], v[12:15]
	v_mfma_f32_16x16x32_bf16 v[8:11], v[160:163], v[204:207], v[8:11]
	v_mfma_f32_16x16x32_bf16 v[54:57], v[208:211], v[172:175], v[54:57]
	v_mfma_f32_16x16x32_bf16 v[50:53], v[216:219], v[172:175], v[50:53]
	v_mfma_f32_16x16x32_bf16 v[38:41], v[208:211], v[184:187], v[38:41]
	v_mfma_f32_16x16x32_bf16 v[34:37], v[216:219], v[184:187], v[34:37]
	v_mfma_f32_16x16x32_bf16 v[20:23], v[208:211], v[192:195], v[20:23]
	v_mfma_f32_16x16x32_bf16 v[16:19], v[216:219], v[192:195], v[16:19]
	v_mfma_f32_16x16x32_bf16 v[4:7], v[208:211], v[200:203], v[4:7]
	v_mfma_f32_16x16x32_bf16 v[0:3], v[216:219], v[200:203], v[0:3]
	v_mfma_f32_16x16x32_bf16 v[54:57], v[212:215], v[180:183], v[54:57]
	v_mfma_f32_16x16x32_bf16 v[50:53], v[220:223], v[180:183], v[50:53]
	v_mfma_f32_16x16x32_bf16 v[38:41], v[212:215], v[188:191], v[38:41]
	v_mfma_f32_16x16x32_bf16 v[34:37], v[220:223], v[188:191], v[34:37]
	v_mfma_f32_16x16x32_bf16 v[20:23], v[212:215], v[196:199], v[20:23]
	v_mfma_f32_16x16x32_bf16 v[16:19], v[220:223], v[196:199], v[16:19]
	v_mfma_f32_16x16x32_bf16 v[4:7], v[212:215], v[204:207], v[4:7]
	v_mfma_f32_16x16x32_bf16 v[0:3], v[220:223], v[204:207], v[0:3]
	s_setprio 0
	s_add_i32 s20, s20, 2
	s_add_u32 s6, s6, 0x100
	s_addc_u32 s7, s7, 0
	s_add_u32 s13, s13, 0x100
	s_addc_u32 s15, s15, 0
	s_cmp_gt_u32 s20, 29
	s_barrier
	s_cbranch_scc0 .LBB0_372
	s_sub_i32 s6, s51, 8
	s_cmp_lt_u32 s6, 8
	s_cbranch_scc1 .Lmain_old
	s_sub_i32 s6, s51, 32
	s_cmp_lt_u32 s6, 12
	s_cbranch_scc1 .Lmain_kv
	v_mbcnt_lo_u32_b32 v217, -1, 0
	v_mbcnt_hi_u32_b32 v217, -1, v217
	v_lshrrev_b32_e32 v208, 4, v217
	v_bfe_u32 v209, v217, 2, 2
	v_and_b32_e32 v210, 3, v217
	v_lshl_add_u32 v216, v208, 2, v209
	v_lshl_add_u32 v217, v210, 4, v216
	v_lshlrev_b32_e32 v217, 2, v217
	v_add_u32_e32 v216, s45, v216
	v_lshlrev_b32_e32 v210, 4, v210
	s_lshl_b32 s6, s44, 6
	v_add_u32_e32 v210, s6, v210
	s_cmp_ge_u32 s51, 0x44
	s_cbranch_scc1 .Lmain_sig
	s_sub_i32 s6, s51, 44
	s_mov_b32 s7, 0x25e51000
	s_mov_b32 s13, 0x15e51000
	s_cmp_lt_i32 s6, 0
	s_cselect_b32 s6, s51, s6
	s_cselect_b32 s7, s13, s7
	s_lshr_b32 s13, s6, 3
	s_lshl_b32 s13, s13, 26
	s_add_i32 s7, s7, s13
	s_and_b32 s6, s6, 7
	s_lshl_b32 s6, s6, 9
	s_add_i32 s7, s7, s6
	s_lshl_b32 s6, s31, 20
	s_add_i32 s7, s7, s6
	s_add_u32 s22, s76, s7
	s_addc_u32 s23, s77, 0
	v_lshl_add_u32 v216, v216, 12, v210
	s_lshr_b32 s6, s51, 3
	s_cmp_eq_u32 s6, 3
	s_cbranch_scc1 .Lmain_q
	s_add_u32 s10, s22, 0
	s_addc_u32 s11, s23, 0
	v_cvt_pk_bf16_f32 v148, v126, v127
	v_cvt_pk_bf16_f32 v149, v128, v129
	v_cvt_pk_bf16_f32 v150, v122, v123
	v_cvt_pk_bf16_f32 v151, v124, v125
	ds_bpermute_b32 v180, v217, v148
	ds_bpermute_b32 v181, v217, v149
	ds_bpermute_b32 v182, v217, v150
	ds_bpermute_b32 v183, v217, v151
	v_cvt_pk_bf16_f32 v152, v118, v119
	v_cvt_pk_bf16_f32 v153, v120, v121
	v_cvt_pk_bf16_f32 v154, v114, v115
	v_cvt_pk_bf16_f32 v155, v116, v117
	ds_bpermute_b32 v184, v217, v152
	ds_bpermute_b32 v185, v217, v153
	ds_bpermute_b32 v186, v217, v154
	ds_bpermute_b32 v187, v217, v155
	s_add_u32 s20, s22, 0x10000
	s_addc_u32 s21, s23, 0
	v_cvt_pk_bf16_f32 v156, v110, v111
	v_cvt_pk_bf16_f32 v157, v112, v113
	v_cvt_pk_bf16_f32 v158, v106, v107
	v_cvt_pk_bf16_f32 v159, v108, v109
	ds_bpermute_b32 v188, v217, v156
	ds_bpermute_b32 v189, v217, v157
	ds_bpermute_b32 v190, v217, v158
	ds_bpermute_b32 v191, v217, v159
	v_cvt_pk_bf16_f32 v160, v102, v103
	v_cvt_pk_bf16_f32 v161, v104, v105
	v_cvt_pk_bf16_f32 v162, v98, v99
	v_cvt_pk_bf16_f32 v163, v100, v101
	ds_bpermute_b32 v192, v217, v160
	ds_bpermute_b32 v193, v217, v161
	ds_bpermute_b32 v194, v217, v162
	ds_bpermute_b32 v195, v217, v163
	s_waitcnt lgkmcnt(0)
	global_store_dwordx4 v216, v[180:183], s[10:11] sc0 sc1
	global_store_dwordx4 v216, v[184:187], s[10:11] offset:256 sc0 sc1
	global_store_dwordx4 v216, v[188:191], s[20:21] sc0 sc1
	global_store_dwordx4 v216, v[192:195], s[20:21] offset:256 sc0 sc1
	s_add_u32 s10, s22, 0x20000
	s_addc_u32 s11, s23, 0
	v_cvt_pk_bf16_f32 v148, v94, v95
	v_cvt_pk_bf16_f32 v149, v96, v97
	v_cvt_pk_bf16_f32 v150, v90, v91
	v_cvt_pk_bf16_f32 v151, v92, v93
	ds_bpermute_b32 v180, v217, v148
	ds_bpermute_b32 v181, v217, v149
	ds_bpermute_b32 v182, v217, v150
	ds_bpermute_b32 v183, v217, v151
	v_cvt_pk_bf16_f32 v152, v86, v87
	v_cvt_pk_bf16_f32 v153, v88, v89
	v_cvt_pk_bf16_f32 v154, v82, v83
	v_cvt_pk_bf16_f32 v155, v84, v85
	ds_bpermute_b32 v184, v217, v152
	ds_bpermute_b32 v185, v217, v153
	ds_bpermute_b32 v186, v217, v154
	ds_bpermute_b32 v187, v217, v155
	s_add_u32 s20, s22, 0x30000
	s_addc_u32 s21, s23, 0
	v_cvt_pk_bf16_f32 v156, v78, v79
	v_cvt_pk_bf16_f32 v157, v80, v81
	v_cvt_pk_bf16_f32 v158, v74, v75
	v_cvt_pk_bf16_f32 v159, v76, v77
	ds_bpermute_b32 v188, v217, v156
	ds_bpermute_b32 v189, v217, v157
	ds_bpermute_b32 v190, v217, v158
	ds_bpermute_b32 v191, v217, v159
	v_cvt_pk_bf16_f32 v160, v70, v71
	v_cvt_pk_bf16_f32 v161, v72, v73
	v_cvt_pk_bf16_f32 v162, v66, v67
	v_cvt_pk_bf16_f32 v163, v68, v69
	ds_bpermute_b32 v192, v217, v160
	ds_bpermute_b32 v193, v217, v161
	ds_bpermute_b32 v194, v217, v162
	ds_bpermute_b32 v195, v217, v163
	s_waitcnt lgkmcnt(0)
	global_store_dwordx4 v216, v[180:183], s[10:11] sc0 sc1
	global_store_dwordx4 v216, v[184:187], s[10:11] offset:256 sc0 sc1
	global_store_dwordx4 v216, v[188:191], s[20:21] sc0 sc1
	global_store_dwordx4 v216, v[192:195], s[20:21] offset:256 sc0 sc1
	s_add_u32 s10, s22, 0x80000
	s_addc_u32 s11, s23, 0
	v_cvt_pk_bf16_f32 v148, v62, v63
	v_cvt_pk_bf16_f32 v149, v64, v65
	v_cvt_pk_bf16_f32 v150, v58, v59
	v_cvt_pk_bf16_f32 v151, v60, v61
	ds_bpermute_b32 v180, v217, v148
	ds_bpermute_b32 v181, v217, v149
	ds_bpermute_b32 v182, v217, v150
	ds_bpermute_b32 v183, v217, v151
	v_cvt_pk_bf16_f32 v152, v54, v55
	v_cvt_pk_bf16_f32 v153, v56, v57
	v_cvt_pk_bf16_f32 v154, v50, v51
	v_cvt_pk_bf16_f32 v155, v52, v53
	ds_bpermute_b32 v184, v217, v152
	ds_bpermute_b32 v185, v217, v153
	ds_bpermute_b32 v186, v217, v154
	ds_bpermute_b32 v187, v217, v155
	s_add_u32 s20, s22, 0x90000
	s_addc_u32 s21, s23, 0
	v_cvt_pk_bf16_f32 v156, v46, v47
	v_cvt_pk_bf16_f32 v157, v48, v49
	v_cvt_pk_bf16_f32 v158, v42, v43
	v_cvt_pk_bf16_f32 v159, v44, v45
	ds_bpermute_b32 v188, v217, v156
	ds_bpermute_b32 v189, v217, v157
	ds_bpermute_b32 v190, v217, v158
	ds_bpermute_b32 v191, v217, v159
	v_cvt_pk_bf16_f32 v160, v38, v39
	v_cvt_pk_bf16_f32 v161, v40, v41
	v_cvt_pk_bf16_f32 v162, v34, v35
	v_cvt_pk_bf16_f32 v163, v36, v37
	ds_bpermute_b32 v192, v217, v160
	ds_bpermute_b32 v193, v217, v161
	ds_bpermute_b32 v194, v217, v162
	ds_bpermute_b32 v195, v217, v163
	s_waitcnt lgkmcnt(0)
	global_store_dwordx4 v216, v[180:183], s[10:11] sc0 sc1
	global_store_dwordx4 v216, v[184:187], s[10:11] offset:256 sc0 sc1
	global_store_dwordx4 v216, v[188:191], s[20:21] sc0 sc1
	global_store_dwordx4 v216, v[192:195], s[20:21] offset:256 sc0 sc1
	s_add_u32 s10, s22, 0xa0000
	s_addc_u32 s11, s23, 0
	v_cvt_pk_bf16_f32 v148, v28, v29
	v_cvt_pk_bf16_f32 v149, v30, v31
	v_cvt_pk_bf16_f32 v150, v24, v25
	v_cvt_pk_bf16_f32 v151, v26, v27
	ds_bpermute_b32 v180, v217, v148
	ds_bpermute_b32 v181, v217, v149
	ds_bpermute_b32 v182, v217, v150
	ds_bpermute_b32 v183, v217, v151
	v_cvt_pk_bf16_f32 v152, v20, v21
	v_cvt_pk_bf16_f32 v153, v22, v23
	v_cvt_pk_bf16_f32 v154, v16, v17
	v_cvt_pk_bf16_f32 v155, v18, v19
	ds_bpermute_b32 v184, v217, v152
	ds_bpermute_b32 v185, v217, v153
	ds_bpermute_b32 v186, v217, v154
	ds_bpermute_b32 v187, v217, v155
	s_add_u32 s20, s22, 0xb0000
	s_addc_u32 s21, s23, 0
	v_cvt_pk_bf16_f32 v156, v12, v13
	v_cvt_pk_bf16_f32 v157, v14, v15
	v_cvt_pk_bf16_f32 v158, v8, v9
	v_cvt_pk_bf16_f32 v159, v10, v11
	ds_bpermute_b32 v188, v217, v156
	ds_bpermute_b32 v189, v217, v157
	ds_bpermute_b32 v190, v217, v158
	ds_bpermute_b32 v191, v217, v159
	v_cvt_pk_bf16_f32 v160, v4, v5
	v_cvt_pk_bf16_f32 v161, v6, v7
	v_cvt_pk_bf16_f32 v162, v0, v1
	v_cvt_pk_bf16_f32 v163, v2, v3
	ds_bpermute_b32 v192, v217, v160
	ds_bpermute_b32 v193, v217, v161
	ds_bpermute_b32 v194, v217, v162
	ds_bpermute_b32 v195, v217, v163
	s_waitcnt lgkmcnt(0)
	global_store_dwordx4 v216, v[180:183], s[10:11] sc0 sc1
	global_store_dwordx4 v216, v[184:187], s[10:11] offset:256 sc0 sc1
	global_store_dwordx4 v216, v[188:191], s[20:21] sc0 sc1
	global_store_dwordx4 v216, v[192:195], s[20:21] offset:256 sc0 sc1
	s_branch .LBB0_364
